# byte-phase pads: in-proj K loop back at offset 0 mod 8 (later loops kept at 0 mod 8)
# baseline (speedup 1.0000x reference)
;     __host__ __device__ bool next(int i, Unit& u) const {
;         const long L = (long)i * G + c; if (L >= nwg) return false;
;         int wgid = (int)L; { const int q = nwg / NXCD, r = nwg % NXCD, xcd = wgid % NXCD, off = wgid / NXCD; wgid = (xcd < r ? xcd * (q + 1) : r * (q + 1) + (xcd - r) * q) + off; }
;         const int nig = WGM * nN, gid = wgid / nig, fm = gid * WGM, gsz = (nM - fm) < WGM ? (nM - fm) : WGM;
;         u.pm = fm + ((wgid % nig) % gsz); u.pn = (wgid % nig) / gsz; return true;
; template <class Epi, class Sched, bool ALIGN_EPI>
; __device__ __forceinline__ void gemm_phase(PG8_LAS unsigned char* lds, const Gemm g, const Sched& S, const Epi& E) {
;     ...
;         const bool has_next = S.next(ui + 1, nxt);
.LBB0_221:
	s_nop 0
	s_add_i32 s15, s15, 1
	s_mul_i32 s2, s15, s31
	s_mul_hi_u32 s3, s15, s64
	s_add_i32 s3, s3, s2
	s_mul_i32 s2, s15, s64
	s_add_u32 s2, s2, s36
	v_readlane_b32 s17, v255, 18
	s_addc_u32 s3, s3, s17
	s_waitcnt lgkmcnt(0)
	v_mov_b64_e32 v[2:3], 0x480
	v_cmp_lt_i64_e64 s[42:43], s[2:3], v[2:3]
	v_mov_b64_e32 v[2:3], 0x47f
	v_cmp_gt_i64_e32 vcc, s[2:3], v[2:3]
	s_cbranch_vccnz .LBB0_223
	s_ashr_i32 s3, s2, 31
	s_lshr_b32 s3, s3, 29
	s_add_i32 s3, s2, s3
	s_ashr_i32 s16, s3, 3
	s_and_b32 s3, s3, -8
	s_sub_i32 s2, s2, s3
	s_cmp_lt_i32 s2, 0
	s_movk_i32 s3, 0x91
	s_cselect_b32 s3, s3, 0x90
	s_mul_i32 s2, s2, s3
	s_add_i32 s2, s2, s16
	s_mul_hi_i32 s3, s2, 0x38e38e39
	s_lshr_b32 s16, s3, 31
	s_ashr_i32 s3, s3, 5
	s_add_i32 s3, s3, s16
	s_lshl_b32 s17, s3, 3
	s_sub_i32 s16, 64, s17
	s_min_i32 s18, s16, 8
	s_abs_i32 s16, s18
	v_cvt_f32_u32_e32 v2, s16
	s_sub_i32 s20, 0, s16
	s_mulk_i32 s3, 0x90
	s_sub_i32 s2, s2, s3
	v_rcp_iflag_f32_e32 v2, v2
	s_abs_i32 s3, s2
	s_xor_b32 s19, s2, s18
	s_ashr_i32 s19, s19, 31
	v_mul_f32_e32 v2, 0x4f7ffffe, v2
	v_cvt_u32_f32_e32 v2, v2
	s_nop 0
	v_readfirstlane_b32 s21, v2
	s_mul_i32 s20, s20, s21
	s_mul_hi_u32 s20, s21, s20
	s_add_i32 s21, s21, s20
	s_mul_hi_u32 s20, s3, s21
	s_mul_i32 s21, s20, s16
	s_sub_i32 s3, s3, s21
	s_add_i32 s22, s20, 1
	s_sub_i32 s21, s3, s16
	s_cmp_ge_u32 s3, s16
	s_cselect_b32 s20, s22, s20
	s_cselect_b32 s3, s21, s3
	s_add_i32 s21, s20, 1
	s_cmp_ge_u32 s3, s16
	s_cselect_b32 s3, s21, s20
	s_xor_b32 s3, s3, s19
	s_sub_i32 s16, s3, s19
	s_mul_i32 s3, s16, s18
	s_sub_i32 s2, s2, s3
	s_add_i32 s18, s17, s2

; #define PG8_WAIT_V(n) asm volatile("s_waitcnt vmcnt(" #n ")" ::: "memory")
; #define PG8_BAR __builtin_amdgcn_s_barrier()
; template <class Epi, class Sched, bool ALIGN_EPI>
; __device__ __forceinline__ void gemm_phase(PG8_LAS unsigned char* lds, const Gemm g, const Sched& S, const Epi& E) {
;     ...
;     PG8_WAIT_V(0);
;     if constexpr (!ALIGN_EPI) { if (wr == 0) PG8_BAR; }
;     PG8_BAR;
.LBB0_311:
	s_waitcnt vmcnt(0)
	v_readlane_b32 s26, v255, 10
	s_barrier
	v_readlane_b32 s27, v255, 11
	s_branch .Lmcv_entry
	s_nop 0
